# P7 epilogue: per-segment address VALU chain (or/ashr/shl64/2x add64) replaced by one preserved base address + store immediate offsets (1 KB steps, one +8 KB base bump)
# baseline (speedup 1.0000x reference)
.LBB0_959:
	s_mov_b32 s98, 0xbfb8aa3b
	s_mov_b32 s99, 0xbfb8aa3b
	v_mul_f32_e32 v153, 0xbfb8aa3b, v124
	v_exp_f32_e32 v153, v153
	v_mul_f32_e32 v154, 0xbfb8aa3b, v125
	v_exp_f32_e32 v156, v154
	v_lshl_add_u32 v146, s18, 8, v148
	v_ashrrev_i32_e32 v147, 31, v146
	v_lshlrev_b64 v[154:155], 6, v[146:147]
	v_add_f32_e32 v147, 1.0, v153
	v_rcp_f32_e32 v147, v147
	v_add_f32_e32 v153, 1.0, v156
	v_rcp_f32_e32 v153, v153
	s_lshl_b32 s11, s19, 2
	v_mul_f32_e32 v124, v124, v147
	v_mul_f32_e32 v124, v124, v116
	v_mul_f32_e32 v116, v125, v153
	v_mul_f32_e32 v125, 0xbfb8aa3b, v126
	v_exp_f32_e32 v125, v125
	v_mul_f32_e32 v147, 0xbfb8aa3b, v127
	v_exp_f32_e32 v147, v147
	v_mul_f32_e32 v153, v116, v117
	v_add_f32_e32 v116, 1.0, v125
	v_rcp_f32_e32 v116, v116
	v_add_f32_e32 v117, 1.0, v147
	v_mul_f32_e32 v125, 0xbfb8aa3b, v120
	v_rcp_f32_e32 v117, v117
	v_exp_f32_e32 v125, v125
	v_mul_f32_e32 v116, v126, v116
	v_mul_f32_e32 v118, v116, v118
	v_mul_f32_e32 v116, v127, v117
	v_add_f32_e32 v117, 1.0, v125
	v_rcp_f32_e32 v117, v117
	v_mul_f32_e32 v125, 0xbfb8aa3b, v121
	v_mul_f32_e32 v119, v116, v119
	v_exp_f32_e32 v125, v125
	v_mul_f32_e32 v116, v120, v117
	v_mul_f32_e32 v120, v116, v112
	v_mul_f32_e32 v116, 0xbfb8aa3b, v122
	v_exp_f32_e32 v116, v116
	v_mul_f32_e32 v117, 0xbfb8aa3b, v123
	v_exp_f32_e32 v117, v117
	v_add_f32_e32 v112, 1.0, v125
	v_rcp_f32_e32 v112, v112
	v_add_f32_e32 v116, 1.0, v116
	v_rcp_f32_e32 v116, v116
	v_add_f32_e32 v117, 1.0, v117
	s_or_b32 s11, s11, s44
	v_rcp_f32_e32 v117, v117
	s_mul_hi_i32 s13, s11, 0x500000
	s_mul_i32 s11, s11, 0x500000
	s_add_u32 s18, s42, s11
	v_mul_f32_e32 v112, v121, v112
	s_addc_u32 s19, s43, s13
	v_mul_f32_e32 v121, v112, v113
	v_mul_f32_e32 v112, v122, v116
	v_lshl_add_u64 v[154:155], s[18:19], 0, v[154:155]
	v_mul_f32_e32 v122, v112, v114
	v_mul_f32_e32 v112, v123, v117
	v_mul_f32_e32 v115, v112, v115
	v_lshl_add_u64 v[116:117], v[154:155], 0, v[136:137]
	v_cvt_pk_bf16_f32 v112, v124, v153
	v_cvt_pk_bf16_f32 v113, v118, v119
	v_cvt_pk_bf16_f32 v114, v120, v121
	v_cvt_pk_bf16_f32 v115, v122, v115
	global_store_dwordx4 v[116:117], v[112:115], off
	s_nop 0
	s_andn2_b64 vcc, exec, s[2:3]
	s_mov_b64 s[2:3], -1
	v_pk_mul_f32 v[112:113], v[108:109], s[98:99]
	v_pk_mul_f32 v[114:115], v[110:111], s[98:99]
	v_pk_mul_f32 v[118:119], v[104:105], s[98:99]
	v_pk_mul_f32 v[120:121], v[106:107], s[98:99]
	v_exp_f32_e32 v112, v112
	v_exp_f32_e32 v113, v113
	v_exp_f32_e32 v114, v114
	v_exp_f32_e32 v115, v115
	v_exp_f32_e32 v118, v118
	v_exp_f32_e32 v119, v119
	v_exp_f32_e32 v120, v120
	v_exp_f32_e32 v121, v121
	v_pk_add_f32 v[112:113], v[112:113], 1.0 op_sel_hi:[1,0]
	v_pk_add_f32 v[114:115], v[114:115], 1.0 op_sel_hi:[1,0]
	v_pk_add_f32 v[118:119], v[118:119], 1.0 op_sel_hi:[1,0]
	v_pk_add_f32 v[120:121], v[120:121], 1.0 op_sel_hi:[1,0]
	v_rcp_f32_e32 v112, v112
	v_rcp_f32_e32 v113, v113
	v_rcp_f32_e32 v114, v114
	v_rcp_f32_e32 v115, v115
	v_rcp_f32_e32 v118, v118
	v_rcp_f32_e32 v119, v119
	v_rcp_f32_e32 v120, v120
	v_rcp_f32_e32 v121, v121
	v_pk_mul_f32 v[108:109], v[108:109], v[112:113]
	v_pk_mul_f32 v[110:111], v[110:111], v[114:115]
	v_pk_mul_f32 v[104:105], v[104:105], v[118:119]
	v_pk_mul_f32 v[106:107], v[106:107], v[120:121]
	v_pk_mul_f32 v[108:109], v[108:109], v[100:101]
	v_pk_mul_f32 v[110:111], v[110:111], v[102:103]
	v_pk_mul_f32 v[104:105], v[104:105], v[96:97]
	v_pk_mul_f32 v[106:107], v[106:107], v[98:99]
	v_cvt_pk_bf16_f32 v96, v108, v109
	v_cvt_pk_bf16_f32 v97, v110, v111
	v_cvt_pk_bf16_f32 v98, v104, v105
	v_cvt_pk_bf16_f32 v99, v106, v107
	global_store_dwordx4 v[116:117], v[96:99], off offset:1024
	s_nop 0
	s_nop 1
	v_pk_mul_f32 v[96:97], v[92:93], s[98:99]
	v_pk_mul_f32 v[98:99], v[94:95], s[98:99]
	v_pk_mul_f32 v[100:101], v[88:89], s[98:99]
	v_pk_mul_f32 v[102:103], v[90:91], s[98:99]
	v_exp_f32_e32 v96, v96
	v_exp_f32_e32 v97, v97
	v_exp_f32_e32 v98, v98
	v_exp_f32_e32 v99, v99
	v_exp_f32_e32 v100, v100
	v_exp_f32_e32 v101, v101
	v_exp_f32_e32 v102, v102
	v_exp_f32_e32 v103, v103
	v_pk_add_f32 v[96:97], v[96:97], 1.0 op_sel_hi:[1,0]
	v_pk_add_f32 v[98:99], v[98:99], 1.0 op_sel_hi:[1,0]
	v_pk_add_f32 v[100:101], v[100:101], 1.0 op_sel_hi:[1,0]
	v_pk_add_f32 v[102:103], v[102:103], 1.0 op_sel_hi:[1,0]
	v_rcp_f32_e32 v96, v96
	v_rcp_f32_e32 v97, v97
	v_rcp_f32_e32 v98, v98
	v_rcp_f32_e32 v99, v99
	v_rcp_f32_e32 v100, v100
	v_rcp_f32_e32 v101, v101
	v_rcp_f32_e32 v102, v102
	v_rcp_f32_e32 v103, v103
	v_pk_mul_f32 v[92:93], v[92:93], v[96:97]
	v_pk_mul_f32 v[94:95], v[94:95], v[98:99]
	v_pk_mul_f32 v[88:89], v[88:89], v[100:101]
	v_pk_mul_f32 v[90:91], v[90:91], v[102:103]
	v_pk_mul_f32 v[92:93], v[92:93], v[84:85]
	v_pk_mul_f32 v[94:95], v[94:95], v[86:87]
	v_pk_mul_f32 v[88:89], v[88:89], v[80:81]
	v_pk_mul_f32 v[90:91], v[90:91], v[82:83]
	v_cvt_pk_bf16_f32 v80, v92, v93
	v_cvt_pk_bf16_f32 v81, v94, v95
	v_cvt_pk_bf16_f32 v82, v88, v89
	v_cvt_pk_bf16_f32 v83, v90, v91
	global_store_dwordx4 v[116:117], v[80:83], off offset:2048
	s_nop 0
	s_nop 1
	v_pk_mul_f32 v[80:81], v[76:77], s[98:99]
	v_pk_mul_f32 v[82:83], v[78:79], s[98:99]
	v_pk_mul_f32 v[84:85], v[72:73], s[98:99]
	v_pk_mul_f32 v[86:87], v[74:75], s[98:99]
	v_exp_f32_e32 v80, v80
	v_exp_f32_e32 v81, v81
	v_exp_f32_e32 v82, v82
	v_exp_f32_e32 v83, v83
	v_exp_f32_e32 v84, v84
	v_exp_f32_e32 v85, v85
	v_exp_f32_e32 v86, v86
	v_exp_f32_e32 v87, v87
	v_pk_add_f32 v[80:81], v[80:81], 1.0 op_sel_hi:[1,0]
	v_pk_add_f32 v[82:83], v[82:83], 1.0 op_sel_hi:[1,0]
	v_pk_add_f32 v[84:85], v[84:85], 1.0 op_sel_hi:[1,0]
	v_pk_add_f32 v[86:87], v[86:87], 1.0 op_sel_hi:[1,0]
	v_rcp_f32_e32 v80, v80
	v_rcp_f32_e32 v81, v81
	v_rcp_f32_e32 v82, v82
	v_rcp_f32_e32 v83, v83
	v_rcp_f32_e32 v84, v84
	v_rcp_f32_e32 v85, v85
	v_rcp_f32_e32 v86, v86
	v_rcp_f32_e32 v87, v87
	v_pk_mul_f32 v[76:77], v[76:77], v[80:81]
	v_pk_mul_f32 v[78:79], v[78:79], v[82:83]
	v_pk_mul_f32 v[72:73], v[72:73], v[84:85]
	v_pk_mul_f32 v[74:75], v[74:75], v[86:87]
	v_pk_mul_f32 v[76:77], v[76:77], v[68:69]
	v_pk_mul_f32 v[78:79], v[78:79], v[70:71]
	v_pk_mul_f32 v[72:73], v[72:73], v[64:65]
	v_pk_mul_f32 v[74:75], v[74:75], v[66:67]
	v_cvt_pk_bf16_f32 v64, v76, v77
	v_cvt_pk_bf16_f32 v65, v78, v79
	v_cvt_pk_bf16_f32 v66, v72, v73
	v_cvt_pk_bf16_f32 v67, v74, v75
	global_store_dwordx4 v[116:117], v[64:67], off offset:3072
	s_nop 0
	s_nop 1
	v_mov_b32_e32 v64, 0x2000
	v_mov_b32_e32 v65, 0
	v_lshl_add_u64 v[116:117], v[116:117], 0, v[64:65]
	v_pk_mul_f32 v[64:65], v[60:61], s[98:99]
	v_pk_mul_f32 v[66:67], v[62:63], s[98:99]
	v_pk_mul_f32 v[68:69], v[56:57], s[98:99]
	v_pk_mul_f32 v[70:71], v[58:59], s[98:99]
	v_exp_f32_e32 v64, v64
	v_exp_f32_e32 v65, v65
	v_exp_f32_e32 v66, v66
	v_exp_f32_e32 v67, v67
	v_exp_f32_e32 v68, v68
	v_exp_f32_e32 v69, v69
	v_exp_f32_e32 v70, v70
	v_exp_f32_e32 v71, v71
	v_pk_add_f32 v[64:65], v[64:65], 1.0 op_sel_hi:[1,0]
	v_pk_add_f32 v[66:67], v[66:67], 1.0 op_sel_hi:[1,0]
	v_pk_add_f32 v[68:69], v[68:69], 1.0 op_sel_hi:[1,0]
	v_pk_add_f32 v[70:71], v[70:71], 1.0 op_sel_hi:[1,0]
	v_rcp_f32_e32 v64, v64
	v_rcp_f32_e32 v65, v65
	v_rcp_f32_e32 v66, v66
	v_rcp_f32_e32 v67, v67
	v_rcp_f32_e32 v68, v68
	v_rcp_f32_e32 v69, v69
	v_rcp_f32_e32 v70, v70
	v_rcp_f32_e32 v71, v71
	v_pk_mul_f32 v[60:61], v[60:61], v[64:65]
	v_pk_mul_f32 v[62:63], v[62:63], v[66:67]
	v_pk_mul_f32 v[56:57], v[56:57], v[68:69]
	v_pk_mul_f32 v[58:59], v[58:59], v[70:71]
	v_pk_mul_f32 v[60:61], v[60:61], v[52:53]
	v_pk_mul_f32 v[62:63], v[62:63], v[54:55]
	v_pk_mul_f32 v[56:57], v[56:57], v[48:49]
	v_pk_mul_f32 v[58:59], v[58:59], v[50:51]
	v_cvt_pk_bf16_f32 v48, v60, v61
	v_cvt_pk_bf16_f32 v49, v62, v63
	v_cvt_pk_bf16_f32 v50, v56, v57
	v_cvt_pk_bf16_f32 v51, v58, v59
	global_store_dwordx4 v[116:117], v[48:51], off offset:0
	s_nop 0
	s_nop 1
	v_pk_mul_f32 v[48:49], v[44:45], s[98:99]
	v_pk_mul_f32 v[50:51], v[46:47], s[98:99]
	v_pk_mul_f32 v[52:53], v[40:41], s[98:99]
	v_pk_mul_f32 v[54:55], v[42:43], s[98:99]
	v_exp_f32_e32 v48, v48
	v_exp_f32_e32 v49, v49
	v_exp_f32_e32 v50, v50
	v_exp_f32_e32 v51, v51
	v_exp_f32_e32 v52, v52
	v_exp_f32_e32 v53, v53
	v_exp_f32_e32 v54, v54
	v_exp_f32_e32 v55, v55
	v_pk_add_f32 v[48:49], v[48:49], 1.0 op_sel_hi:[1,0]
	v_pk_add_f32 v[50:51], v[50:51], 1.0 op_sel_hi:[1,0]
	v_pk_add_f32 v[52:53], v[52:53], 1.0 op_sel_hi:[1,0]
	v_pk_add_f32 v[54:55], v[54:55], 1.0 op_sel_hi:[1,0]
	v_rcp_f32_e32 v48, v48
	v_rcp_f32_e32 v49, v49
	v_rcp_f32_e32 v50, v50
	v_rcp_f32_e32 v51, v51
	v_rcp_f32_e32 v52, v52
	v_rcp_f32_e32 v53, v53
	v_rcp_f32_e32 v54, v54
	v_rcp_f32_e32 v55, v55
	v_pk_mul_f32 v[44:45], v[44:45], v[48:49]
	v_pk_mul_f32 v[46:47], v[46:47], v[50:51]
	v_pk_mul_f32 v[40:41], v[40:41], v[52:53]
	v_pk_mul_f32 v[42:43], v[42:43], v[54:55]
	v_pk_mul_f32 v[44:45], v[44:45], v[36:37]
	v_pk_mul_f32 v[46:47], v[46:47], v[38:39]
	v_pk_mul_f32 v[40:41], v[40:41], v[32:33]
	v_pk_mul_f32 v[42:43], v[42:43], v[34:35]
	v_cvt_pk_bf16_f32 v32, v44, v45
	v_cvt_pk_bf16_f32 v33, v46, v47
	v_cvt_pk_bf16_f32 v34, v40, v41
	v_cvt_pk_bf16_f32 v35, v42, v43
	global_store_dwordx4 v[116:117], v[32:35], off offset:1024
	s_nop 0
	s_nop 1
	v_pk_mul_f32 v[32:33], v[28:29], s[98:99]
	v_pk_mul_f32 v[34:35], v[30:31], s[98:99]
	v_pk_mul_f32 v[36:37], v[24:25], s[98:99]
	v_pk_mul_f32 v[38:39], v[26:27], s[98:99]
	v_exp_f32_e32 v32, v32
	v_exp_f32_e32 v33, v33
	v_exp_f32_e32 v34, v34
	v_exp_f32_e32 v35, v35
	v_exp_f32_e32 v36, v36
	v_exp_f32_e32 v37, v37
	v_exp_f32_e32 v38, v38
	v_exp_f32_e32 v39, v39
	v_pk_add_f32 v[32:33], v[32:33], 1.0 op_sel_hi:[1,0]
	v_pk_add_f32 v[34:35], v[34:35], 1.0 op_sel_hi:[1,0]
	v_pk_add_f32 v[36:37], v[36:37], 1.0 op_sel_hi:[1,0]
	v_pk_add_f32 v[38:39], v[38:39], 1.0 op_sel_hi:[1,0]
	v_rcp_f32_e32 v32, v32
	v_rcp_f32_e32 v33, v33
	v_rcp_f32_e32 v34, v34
	v_rcp_f32_e32 v35, v35
	v_rcp_f32_e32 v36, v36
	v_rcp_f32_e32 v37, v37
	v_rcp_f32_e32 v38, v38
	v_rcp_f32_e32 v39, v39
	v_pk_mul_f32 v[28:29], v[28:29], v[32:33]
	v_pk_mul_f32 v[30:31], v[30:31], v[34:35]
	v_pk_mul_f32 v[24:25], v[24:25], v[36:37]
	v_pk_mul_f32 v[26:27], v[26:27], v[38:39]
	v_pk_mul_f32 v[28:29], v[28:29], v[20:21]
	v_pk_mul_f32 v[30:31], v[30:31], v[22:23]
	v_pk_mul_f32 v[24:25], v[24:25], v[16:17]
	v_pk_mul_f32 v[26:27], v[26:27], v[18:19]
	v_cvt_pk_bf16_f32 v16, v28, v29
	v_cvt_pk_bf16_f32 v17, v30, v31
	v_cvt_pk_bf16_f32 v18, v24, v25
	v_cvt_pk_bf16_f32 v19, v26, v27
	global_store_dwordx4 v[116:117], v[16:19], off offset:2048
	s_nop 0
	s_nop 1
	v_pk_mul_f32 v[16:17], v[12:13], s[98:99]
	v_pk_mul_f32 v[18:19], v[14:15], s[98:99]
	v_pk_mul_f32 v[20:21], v[8:9], s[98:99]
	v_pk_mul_f32 v[22:23], v[10:11], s[98:99]
	v_exp_f32_e32 v16, v16
	v_exp_f32_e32 v17, v17
	v_exp_f32_e32 v18, v18
	v_exp_f32_e32 v19, v19
	v_exp_f32_e32 v20, v20
	v_exp_f32_e32 v21, v21
	v_exp_f32_e32 v22, v22
	v_exp_f32_e32 v23, v23
	v_pk_add_f32 v[16:17], v[16:17], 1.0 op_sel_hi:[1,0]
	v_pk_add_f32 v[18:19], v[18:19], 1.0 op_sel_hi:[1,0]
	v_pk_add_f32 v[20:21], v[20:21], 1.0 op_sel_hi:[1,0]
	v_pk_add_f32 v[22:23], v[22:23], 1.0 op_sel_hi:[1,0]
	v_rcp_f32_e32 v16, v16
	v_rcp_f32_e32 v17, v17
	v_rcp_f32_e32 v18, v18
	v_rcp_f32_e32 v19, v19
	v_rcp_f32_e32 v20, v20
	v_rcp_f32_e32 v21, v21
	v_rcp_f32_e32 v22, v22
	v_rcp_f32_e32 v23, v23
	v_pk_mul_f32 v[12:13], v[12:13], v[16:17]
	v_pk_mul_f32 v[14:15], v[14:15], v[18:19]
	v_pk_mul_f32 v[8:9], v[8:9], v[20:21]
	v_pk_mul_f32 v[10:11], v[10:11], v[22:23]
	v_pk_mul_f32 v[12:13], v[12:13], v[4:5]
	v_pk_mul_f32 v[14:15], v[14:15], v[6:7]
	v_pk_mul_f32 v[8:9], v[8:9], v[0:1]
	v_pk_mul_f32 v[10:11], v[10:11], v[2:3]
	v_cvt_pk_bf16_f32 v0, v12, v13
	v_cvt_pk_bf16_f32 v1, v14, v15
	v_cvt_pk_bf16_f32 v2, v8, v9
	v_cvt_pk_bf16_f32 v3, v10, v11
	global_store_dwordx4 v[116:117], v[0:3], off offset:3072
	s_cbranch_vccnz .LBB0_952
	s_andn2_b64 vcc, exec, s[4:5]
	s_cbranch_vccnz .LBB0_951
	s_barrier
	s_branch .LBB0_951
